# S5 post pass: table-fragment loads of the G' pass issued five steps ahead; plus S5 pre deep prefetch, vres block, rstd pipelining, PRM overlap
# baseline (speedup 1.0000x reference)
; #define SB() __builtin_amdgcn_sched_barrier(0)
; template <bool POST>
; DI void s5_phase(const Frame& F, const CAS Args& a, int l, int first, int stride) {
;     ...
;         { bf16x8 gf[2][4];
; #pragma unroll
;           for (int ks = 0; ks < 4; ++ks) gf[0][ks] = LDU(bf16x8, tb + S5T_G + (0 * 4 + ks) * 1024, ltab);
; #pragma unroll
;           for (int mt = 0; mt < 8; ++mt) {
;               if (mt + 1 < 8) {
; #pragma unroll
;                   for (int ks = 0; ks < 4; ++ks) gf[(mt + 1) & 1][ks] = LDU(bf16x8, tb + S5T_G + ((mt + 1) * 4 + ks) * 1024, ltab); }
;               SB();
;               f32x4 acc = {0.f, 0.f, 0.f, 0.f};
; #pragma unroll
;               for (int ks = 0; ks < 4; ++ks) acc = __builtin_amdgcn_mfma_f32_16x16x32_bf16(gf[mt & 1][ks], uf[ks], acc, 0, 0, 0);
;               if (mt < 4) Yr[mt] = acc; else Yi[mt - 4] = acc;
;               SB(); } }
.LBB0_796:
	v_mov_b32_e32 v49, v185
	v_lshl_add_u64 v[90:91], s[18:19], 0, v[48:49]
	v_mov_b32_e32 v139, v48
	global_load_dwordx4 v[140:143], v139, s[18:19]
	global_load_dwordx4 v[144:147], v139, s[18:19] offset:1024
	global_load_dwordx4 v[148:151], v139, s[18:19] offset:2048
	global_load_dwordx4 v[152:155], v139, s[18:19] offset:3072
	s_add_u32 s98, s18, 0x1000
	s_addc_u32 s99, s19, 0
	global_load_dwordx4 v[156:159], v139, s[98:99]
	global_load_dwordx4 v[160:163], v139, s[98:99] offset:1024
	global_load_dwordx4 v[164:167], v139, s[98:99] offset:2048
	global_load_dwordx4 v[168:171], v139, s[98:99] offset:3072
	s_add_u32 s98, s18, 0x2000
	s_addc_u32 s99, s19, 0
	global_load_dwordx4 v[172:175], v139, s[98:99]
	global_load_dwordx4 v[176:179], v139, s[98:99] offset:1024
	global_load_dwordx4 v[180:183], v139, s[98:99] offset:2048
	global_load_dwordx4 v[188:191], v139, s[98:99] offset:3072
	s_add_u32 s98, s18, 0x3000
	s_addc_u32 s99, s19, 0
	global_load_dwordx4 v[196:199], v139, s[98:99]
	global_load_dwordx4 v[200:203], v139, s[98:99] offset:1024
	global_load_dwordx4 v[204:207], v139, s[98:99] offset:2048
	global_load_dwordx4 v[208:211], v139, s[98:99] offset:3072
	s_add_u32 s98, s18, 0x4000
	s_addc_u32 s99, s19, 0
	global_load_dwordx4 v[212:215], v139, s[98:99]
	global_load_dwordx4 v[216:219], v139, s[98:99] offset:1024
	global_load_dwordx4 v[220:223], v139, s[98:99] offset:2048
	global_load_dwordx4 v[234:237], v139, s[98:99] offset:3072
	s_waitcnt vmcnt(19)
	v_mfma_f32_16x16x32_bf16 v[48:51], v[140:143], v[32:35], 0
	s_waitcnt vmcnt(18)
	v_mfma_f32_16x16x32_bf16 v[48:51], v[144:147], v[36:39], v[48:51]
	s_waitcnt vmcnt(17)
	v_mfma_f32_16x16x32_bf16 v[48:51], v[148:151], v[40:43], v[48:51]
	s_waitcnt vmcnt(16)
	v_mfma_f32_16x16x32_bf16 v[48:51], v[152:155], v[44:47], v[48:51]
	s_add_u32 s98, s18, 0x5000
	s_addc_u32 s99, s19, 0
	global_load_dwordx4 v[140:143], v139, s[98:99]
	global_load_dwordx4 v[144:147], v139, s[98:99] offset:1024
	global_load_dwordx4 v[148:151], v139, s[98:99] offset:2048
	global_load_dwordx4 v[152:155], v139, s[98:99] offset:3072
	s_waitcnt vmcnt(19)
	v_mfma_f32_16x16x32_bf16 v[64:67], v[156:159], v[32:35], 0
	s_waitcnt vmcnt(18)
	v_mfma_f32_16x16x32_bf16 v[64:67], v[160:163], v[36:39], v[64:67]
	s_waitcnt vmcnt(17)
	v_mfma_f32_16x16x32_bf16 v[64:67], v[164:167], v[40:43], v[64:67]
	s_waitcnt vmcnt(16)
	v_mfma_f32_16x16x32_bf16 v[64:67], v[168:171], v[44:47], v[64:67]
	s_add_u32 s98, s18, 0x6000
	s_addc_u32 s99, s19, 0
	global_load_dwordx4 v[156:159], v139, s[98:99]
	global_load_dwordx4 v[160:163], v139, s[98:99] offset:1024
	global_load_dwordx4 v[164:167], v139, s[98:99] offset:2048
	global_load_dwordx4 v[168:171], v139, s[98:99] offset:3072
	s_waitcnt vmcnt(19)
	v_mfma_f32_16x16x32_bf16 v[52:55], v[172:175], v[32:35], 0
	s_waitcnt vmcnt(18)
	v_mfma_f32_16x16x32_bf16 v[52:55], v[176:179], v[36:39], v[52:55]
	s_waitcnt vmcnt(17)
	v_mfma_f32_16x16x32_bf16 v[52:55], v[180:183], v[40:43], v[52:55]
	s_waitcnt vmcnt(16)
	v_mfma_f32_16x16x32_bf16 v[52:55], v[188:191], v[44:47], v[52:55]
	s_add_u32 s98, s18, 0x7000
	s_addc_u32 s99, s19, 0
	global_load_dwordx4 v[172:175], v139, s[98:99]
	global_load_dwordx4 v[176:179], v139, s[98:99] offset:1024
	global_load_dwordx4 v[180:183], v139, s[98:99] offset:2048
	global_load_dwordx4 v[188:191], v139, s[98:99] offset:3072
	s_waitcnt vmcnt(19)
	v_mfma_f32_16x16x32_bf16 v[68:71], v[196:199], v[32:35], 0
	s_waitcnt vmcnt(18)
	v_mfma_f32_16x16x32_bf16 v[68:71], v[200:203], v[36:39], v[68:71]
	s_waitcnt vmcnt(17)
	v_mfma_f32_16x16x32_bf16 v[68:71], v[204:207], v[40:43], v[68:71]
	s_waitcnt vmcnt(16)
	v_mfma_f32_16x16x32_bf16 v[68:71], v[208:211], v[44:47], v[68:71]
	s_waitcnt vmcnt(15)
	v_mfma_f32_16x16x32_bf16 v[56:59], v[212:215], v[32:35], 0
	s_waitcnt vmcnt(14)
	v_mfma_f32_16x16x32_bf16 v[56:59], v[216:219], v[36:39], v[56:59]
	s_waitcnt vmcnt(13)
	v_mfma_f32_16x16x32_bf16 v[56:59], v[220:223], v[40:43], v[56:59]
	s_waitcnt vmcnt(12)
	v_mfma_f32_16x16x32_bf16 v[56:59], v[234:237], v[44:47], v[56:59]
	s_waitcnt vmcnt(11)
	v_mfma_f32_16x16x32_bf16 v[72:75], v[140:143], v[32:35], 0
	s_waitcnt vmcnt(10)
	v_mfma_f32_16x16x32_bf16 v[72:75], v[144:147], v[36:39], v[72:75]
	s_waitcnt vmcnt(9)
	v_mfma_f32_16x16x32_bf16 v[72:75], v[148:151], v[40:43], v[72:75]
	s_waitcnt vmcnt(8)
	v_mfma_f32_16x16x32_bf16 v[72:75], v[152:155], v[44:47], v[72:75]
	s_waitcnt vmcnt(7)
	v_mfma_f32_16x16x32_bf16 v[60:63], v[156:159], v[32:35], 0
	s_waitcnt vmcnt(6)
	v_mfma_f32_16x16x32_bf16 v[60:63], v[160:163], v[36:39], v[60:63]
	s_waitcnt vmcnt(5)
	v_mfma_f32_16x16x32_bf16 v[60:63], v[164:167], v[40:43], v[60:63]
	s_waitcnt vmcnt(4)
	v_mfma_f32_16x16x32_bf16 v[60:63], v[168:171], v[44:47], v[60:63]
	s_waitcnt vmcnt(3)
	v_mfma_f32_16x16x32_bf16 v[32:35], v[172:175], v[32:35], 0
	s_waitcnt vmcnt(2)
	v_mfma_f32_16x16x32_bf16 v[32:35], v[176:179], v[36:39], v[32:35]
	s_waitcnt vmcnt(1)
	v_mfma_f32_16x16x32_bf16 v[32:35], v[180:183], v[40:43], v[32:35]
	s_waitcnt vmcnt(0)
; #define SB() __builtin_amdgcn_sched_barrier(0)
; template <int CTRL> DI f32x4 dpp4(const f32x4 v) { const float a0 = v[0], a1 = v[1], a2 = v[2], a3 = v[3]; const float b0 = DPPF(a0, CTRL), b1 = DPPF(a1, CTRL), b2 = DPPF(a2, CTRL), b3 = DPPF(a3, CTRL); return (f32x4){b0, b1, b2, b3}; }
; template <int D>
; DI void s5_scan_step(f32x4 (&Yr)[4], f32x4 (&Yi)[4], f32x4 (&Ar)[4], f32x4 (&Ai)[4]) {
; #pragma unroll
;     for (int m = 0; m < 4; ++m) {
;         const f32x4 sr = dpp4<0x110 + D>(Yr[m]), si = dpp4<0x110 + D>(Yi[m]);
;         Yr[m] += Ar[m] * sr - Ai[m] * si; Yi[m] += Ar[m] * si + Ai[m] * sr;
;         const f32x4 a2r = Ar[m] * Ar[m] - Ai[m] * Ai[m], a2i = 2.f * Ar[m] * Ai[m]; Ar[m] = a2r; Ai[m] = a2i; }
; }
; template <bool POST>
; DI void s5_phase(const Frame& F, const CAS Args& a, int l, int first, int stride) {
;     ...
;           for (int mt = 0; mt < 8; ++mt) {
;               if (mt + 1 < 8) {
; #pragma unroll
;                   for (int ks = 0; ks < 4; ++ks) gf[(mt + 1) & 1][ks] = LDU(bf16x8, tb + S5T_G + ((mt + 1) * 4 + ks) * 1024, ltab); }
;               SB();
;               f32x4 acc = {0.f, 0.f, 0.f, 0.f};
; #pragma unroll
;               for (int ks = 0; ks < 4; ++ks) acc = __builtin_amdgcn_mfma_f32_16x16x32_bf16(gf[mt & 1][ks], uf[ks], acc, 0, 0, 0);
;               if (mt < 4) Yr[mt] = acc; else Yi[mt - 4] = acc;
;               SB(); } }
	v_mfma_f32_16x16x32_bf16 v[36:39], v[188:191], v[44:47], v[32:35]
	s_movk_i32 s0, 0x6000
	v_mov_b32_dpp v40, v56 row_shr:1 row_mask:0xf bank_mask:0xf bound_ctrl:1
	v_mov_b32_dpp v41, v57 row_shr:1 row_mask:0xf bank_mask:0xf bound_ctrl:1
	v_mov_b32_dpp v42, v58 row_shr:1 row_mask:0xf bank_mask:0xf bound_ctrl:1
	v_mov_b32_dpp v43, v59 row_shr:1 row_mask:0xf bank_mask:0xf bound_ctrl:1
	s_nop 1
	v_mov_b32_dpp v32, v48 row_shr:1 row_mask:0xf bank_mask:0xf bound_ctrl:1
	v_mov_b32_dpp v33, v49 row_shr:1 row_mask:0xf bank_mask:0xf bound_ctrl:1
	v_mov_b32_dpp v34, v50 row_shr:1 row_mask:0xf bank_mask:0xf bound_ctrl:1
	v_mov_b32_dpp v35, v51 row_shr:1 row_mask:0xf bank_mask:0xf bound_ctrl:1
	v_pk_mul_f32 v[44:45], v[26:27], v[42:43]
	v_pk_mul_f32 v[46:47], v[24:25], v[40:41]
	v_pk_mul_f32 v[42:43], v[30:31], v[42:43]
	v_pk_mul_f32 v[40:41], v[28:29], v[40:41]
	v_pk_fma_f32 v[46:47], v[28:29], v[32:33], v[46:47] neg_lo:[0,0,1] neg_hi:[0,0,1]
	v_pk_fma_f32 v[44:45], v[30:31], v[34:35], v[44:45] neg_lo:[0,0,1] neg_hi:[0,0,1]
	v_pk_fma_f32 v[32:33], v[24:25], v[32:33], v[40:41]
	v_pk_fma_f32 v[34:35], v[26:27], v[34:35], v[42:43]
	v_pk_add_f32 v[42:43], v[56:57], v[32:33]
	v_pk_add_f32 v[40:41], v[58:59], v[34:35]
	v_pk_mul_f32 v[34:35], v[26:27], v[26:27]
	v_pk_mul_f32 v[56:57], v[24:25], v[24:25]
	v_pk_mul_f32 v[58:59], v[4:5], v[4:5]
	v_pk_fma_f32 v[96:97], v[30:31], v[30:31], v[34:35] neg_lo:[0,0,1] neg_hi:[0,0,1]
	v_pk_fma_f32 v[34:35], v[0:1], v[0:1], v[58:59] neg_lo:[0,0,1] neg_hi:[0,0,1]
	v_pk_fma_f32 v[56:57], v[28:29], v[28:29], v[56:57] neg_lo:[0,0,1] neg_hi:[0,0,1]
	v_pk_add_f32 v[28:29], v[28:29], v[28:29]
	v_mov_b32_dpp v58, v72 row_shr:1 row_mask:0xf bank_mask:0xf bound_ctrl:1
	v_mov_b32_dpp v59, v73 row_shr:1 row_mask:0xf bank_mask:0xf bound_ctrl:1
	v_pk_mul_f32 v[78:79], v[20:21], v[20:21]
	v_pk_add_f32 v[30:31], v[30:31], v[30:31]
	v_pk_mul_f32 v[24:25], v[24:25], v[28:29]
	v_mov_b32_dpp v28, v64 row_shr:1 row_mask:0xf bank_mask:0xf bound_ctrl:1
	v_mov_b32_dpp v29, v65 row_shr:1 row_mask:0xf bank_mask:0xf bound_ctrl:1
	v_mov_b32_dpp v98, v74 row_shr:1 row_mask:0xf bank_mask:0xf bound_ctrl:1
	v_mov_b32_dpp v99, v75 row_shr:1 row_mask:0xf bank_mask:0xf bound_ctrl:1
	v_pk_mul_f32 v[102:103], v[20:21], v[58:59]
	v_pk_mul_f32 v[58:59], v[16:17], v[58:59]
	v_pk_add_f32 v[44:45], v[50:51], v[44:45]
	v_pk_mul_f32 v[50:51], v[22:23], v[22:23]
	v_pk_fma_f32 v[78:79], v[16:17], v[16:17], v[78:79] neg_lo:[0,0,1] neg_hi:[0,0,1]
	v_pk_mul_f32 v[26:27], v[26:27], v[30:31]
	v_mov_b32_dpp v30, v66 row_shr:1 row_mask:0xf bank_mask:0xf bound_ctrl:1
	v_mov_b32_dpp v31, v67 row_shr:1 row_mask:0xf bank_mask:0xf bound_ctrl:1
	v_pk_mul_f32 v[100:101], v[22:23], v[98:99]
	v_pk_fma_f32 v[102:103], v[16:17], v[28:29], v[102:103] neg_lo:[0,0,1] neg_hi:[0,0,1]
	v_pk_mul_f32 v[98:99], v[18:19], v[98:99]
	v_pk_fma_f32 v[28:29], v[20:21], v[28:29], v[58:59]
	v_pk_add_f32 v[16:17], v[16:17], v[16:17]
	v_mov_b32_dpp v58, v60 row_shr:1 row_mask:0xf bank_mask:0xf bound_ctrl:1
	v_mov_b32_dpp v59, v61 row_shr:1 row_mask:0xf bank_mask:0xf bound_ctrl:1
	v_pk_fma_f32 v[50:51], v[18:19], v[18:19], v[50:51] neg_lo:[0,0,1] neg_hi:[0,0,1]
	v_pk_fma_f32 v[100:101], v[18:19], v[30:31], v[100:101] neg_lo:[0,0,1] neg_hi:[0,0,1]
	v_pk_fma_f32 v[30:31], v[22:23], v[30:31], v[98:99]
	v_pk_add_f32 v[28:29], v[72:73], v[28:29]
	v_pk_add_f32 v[18:19], v[18:19], v[18:19]
	v_pk_mul_f32 v[16:17], v[20:21], v[16:17]
	v_mov_b32_dpp v20, v52 row_shr:1 row_mask:0xf bank_mask:0xf bound_ctrl:1
	v_mov_b32_dpp v21, v53 row_shr:1 row_mask:0xf bank_mask:0xf bound_ctrl:1
	v_mov_b32_dpp v72, v62 row_shr:1 row_mask:0xf bank_mask:0xf bound_ctrl:1
	v_mov_b32_dpp v73, v63 row_shr:1 row_mask:0xf bank_mask:0xf bound_ctrl:1
	v_pk_mul_f32 v[98:99], v[12:13], v[58:59]
	v_pk_mul_f32 v[58:59], v[8:9], v[58:59]
	v_pk_add_f32 v[46:47], v[48:49], v[46:47]
	v_pk_mul_f32 v[48:49], v[14:15], v[14:15]
	v_pk_mul_f32 v[76:77], v[12:13], v[12:13]
	v_pk_add_f32 v[30:31], v[74:75], v[30:31]
	v_pk_mul_f32 v[18:19], v[22:23], v[18:19]
	v_mov_b32_dpp v22, v54 row_shr:1 row_mask:0xf bank_mask:0xf bound_ctrl:1
	v_mov_b32_dpp v23, v55 row_shr:1 row_mask:0xf bank_mask:0xf bound_ctrl:1
	v_pk_mul_f32 v[74:75], v[14:15], v[72:73]
	v_pk_fma_f32 v[98:99], v[8:9], v[20:21], v[98:99] neg_lo:[0,0,1] neg_hi:[0,0,1]
	v_pk_mul_f32 v[72:73], v[10:11], v[72:73]
	v_pk_fma_f32 v[20:21], v[12:13], v[20:21], v[58:59]
	v_pk_fma_f32 v[48:49], v[10:11], v[10:11], v[48:49] neg_lo:[0,0,1] neg_hi:[0,0,1]
	v_pk_fma_f32 v[76:77], v[8:9], v[8:9], v[76:77] neg_lo:[0,0,1] neg_hi:[0,0,1]
	v_pk_fma_f32 v[74:75], v[10:11], v[22:23], v[74:75] neg_lo:[0,0,1] neg_hi:[0,0,1]
	v_pk_fma_f32 v[22:23], v[14:15], v[22:23], v[72:73]
	v_pk_add_f32 v[20:21], v[60:61], v[20:21]
	v_pk_add_f32 v[10:11], v[10:11], v[10:11]
	v_pk_add_f32 v[8:9], v[8:9], v[8:9]
	v_mov_b32_dpp v58, v36 row_shr:1 row_mask:0xf bank_mask:0xf bound_ctrl:1
	v_mov_b32_dpp v59, v37 row_shr:1 row_mask:0xf bank_mask:0xf bound_ctrl:1
	v_mov_b32_dpp v60, v38 row_shr:1 row_mask:0xf bank_mask:0xf bound_ctrl:1
	v_mov_b32_dpp v61, v39 row_shr:1 row_mask:0xf bank_mask:0xf bound_ctrl:1
	v_pk_mul_f32 v[32:33], v[6:7], v[6:7]
	v_pk_add_f32 v[22:23], v[62:63], v[22:23]
	v_pk_mul_f32 v[10:11], v[14:15], v[10:11]
	v_pk_mul_f32 v[8:9], v[12:13], v[8:9]
	v_mov_b32_dpp v12, v68 row_shr:1 row_mask:0xf bank_mask:0xf bound_ctrl:1
	v_mov_b32_dpp v13, v69 row_shr:1 row_mask:0xf bank_mask:0xf bound_ctrl:1
	v_mov_b32_dpp v14, v70 row_shr:1 row_mask:0xf bank_mask:0xf bound_ctrl:1
	v_mov_b32_dpp v15, v71 row_shr:1 row_mask:0xf bank_mask:0xf bound_ctrl:1
	v_pk_mul_f32 v[62:63], v[6:7], v[60:61]
	v_pk_mul_f32 v[72:73], v[4:5], v[58:59]
; template <int CTRL> DI f32x4 dpp4(const f32x4 v) { const float a0 = v[0], a1 = v[1], a2 = v[2], a3 = v[3]; const float b0 = DPPF(a0, CTRL), b1 = DPPF(a1, CTRL), b2 = DPPF(a2, CTRL), b3 = DPPF(a3, CTRL); return (f32x4){b0, b1, b2, b3}; }
; template <int D>
; DI void s5_scan_step(f32x4 (&Yr)[4], f32x4 (&Yi)[4], f32x4 (&Ar)[4], f32x4 (&Ai)[4]) {
; #pragma unroll
;     for (int m = 0; m < 4; ++m) {
;         const f32x4 sr = dpp4<0x110 + D>(Yr[m]), si = dpp4<0x110 + D>(Yi[m]);
;         Yr[m] += Ar[m] * sr - Ai[m] * si; Yi[m] += Ar[m] * si + Ai[m] * sr;
;         const f32x4 a2r = Ar[m] * Ar[m] - Ai[m] * Ai[m], a2i = 2.f * Ar[m] * Ai[m]; Ar[m] = a2r; Ai[m] = a2i; }
; }
	v_pk_mul_f32 v[60:61], v[2:3], v[60:61]
	v_pk_mul_f32 v[58:59], v[0:1], v[58:59]
	v_pk_fma_f32 v[32:33], v[2:3], v[2:3], v[32:33] neg_lo:[0,0,1] neg_hi:[0,0,1]
	v_pk_fma_f32 v[72:73], v[0:1], v[12:13], v[72:73] neg_lo:[0,0,1] neg_hi:[0,0,1]
	v_pk_fma_f32 v[62:63], v[2:3], v[14:15], v[62:63] neg_lo:[0,0,1] neg_hi:[0,0,1]
	v_pk_fma_f32 v[12:13], v[4:5], v[12:13], v[58:59]
	v_pk_fma_f32 v[14:15], v[6:7], v[14:15], v[60:61]
	v_pk_add_f32 v[2:3], v[2:3], v[2:3]
	v_pk_add_f32 v[0:1], v[0:1], v[0:1]
	v_pk_add_f32 v[66:67], v[66:67], v[100:101]
	v_pk_add_f32 v[64:65], v[64:65], v[102:103]
	v_pk_add_f32 v[54:55], v[54:55], v[74:75]
	v_pk_add_f32 v[52:53], v[52:53], v[98:99]
	v_pk_add_f32 v[14:15], v[38:39], v[14:15]
	v_pk_add_f32 v[12:13], v[36:37], v[12:13]
	v_pk_mul_f32 v[2:3], v[6:7], v[2:3]
	v_pk_mul_f32 v[0:1], v[4:5], v[0:1]
	v_pk_add_f32 v[62:63], v[70:71], v[62:63]
	v_pk_add_f32 v[68:69], v[68:69], v[72:73]
	v_mov_b32_dpp v36, v42 row_shr:2 row_mask:0xf bank_mask:0xf bound_ctrl:1
	v_mov_b32_dpp v37, v43 row_shr:2 row_mask:0xf bank_mask:0xf bound_ctrl:1
	v_mov_b32_dpp v4, v46 row_shr:2 row_mask:0xf bank_mask:0xf bound_ctrl:1
	v_mov_b32_dpp v5, v47 row_shr:2 row_mask:0xf bank_mask:0xf bound_ctrl:1
	v_mov_b32_dpp v38, v40 row_shr:2 row_mask:0xf bank_mask:0xf bound_ctrl:1
	v_mov_b32_dpp v39, v41 row_shr:2 row_mask:0xf bank_mask:0xf bound_ctrl:1
	v_pk_mul_f32 v[60:61], v[24:25], v[36:37]
	v_pk_mul_f32 v[36:37], v[56:57], v[36:37]
	v_mov_b32_dpp v6, v44 row_shr:2 row_mask:0xf bank_mask:0xf bound_ctrl:1
	v_mov_b32_dpp v7, v45 row_shr:2 row_mask:0xf bank_mask:0xf bound_ctrl:1
	v_pk_mul_f32 v[58:59], v[26:27], v[38:39]
	v_pk_fma_f32 v[60:61], v[56:57], v[4:5], v[60:61] neg_lo:[0,0,1] neg_hi:[0,0,1]
	v_pk_fma_f32 v[4:5], v[24:25], v[4:5], v[36:37]
	v_pk_fma_f32 v[58:59], v[96:97], v[6:7], v[58:59] neg_lo:[0,0,1] neg_hi:[0,0,1]
	v_pk_mul_f32 v[38:39], v[96:97], v[38:39]
	v_pk_add_f32 v[4:5], v[42:43], v[4:5]
	v_pk_mul_f32 v[42:43], v[96:97], v[96:97]
	v_pk_mul_f32 v[72:73], v[56:57], v[56:57]
	v_pk_add_f32 v[74:75], v[96:97], v[96:97]
	v_pk_add_f32 v[56:57], v[56:57], v[56:57]
	v_mov_b32_dpp v96, v28 row_shr:2 row_mask:0xf bank_mask:0xf bound_ctrl:1
	v_mov_b32_dpp v97, v29 row_shr:2 row_mask:0xf bank_mask:0xf bound_ctrl:1
	v_mov_b32_dpp v98, v30 row_shr:2 row_mask:0xf bank_mask:0xf bound_ctrl:1
	v_mov_b32_dpp v99, v31 row_shr:2 row_mask:0xf bank_mask:0xf bound_ctrl:1
	v_pk_fma_f32 v[6:7], v[26:27], v[6:7], v[38:39]
	v_pk_fma_f32 v[42:43], v[26:27], v[26:27], v[42:43] neg_lo:[1,0,0] neg_hi:[1,0,0]
	v_pk_fma_f32 v[72:73], v[24:25], v[24:25], v[72:73] neg_lo:[1,0,0] neg_hi:[1,0,0]
	v_pk_mul_f32 v[26:27], v[26:27], v[74:75]
	v_pk_mul_f32 v[24:25], v[24:25], v[56:57]
	v_mov_b32_dpp v56, v64 row_shr:2 row_mask:0xf bank_mask:0xf bound_ctrl:1
	v_mov_b32_dpp v57, v65 row_shr:2 row_mask:0xf bank_mask:0xf bound_ctrl:1
	v_mov_b32_dpp v74, v66 row_shr:2 row_mask:0xf bank_mask:0xf bound_ctrl:1
	v_mov_b32_dpp v75, v67 row_shr:2 row_mask:0xf bank_mask:0xf bound_ctrl:1
	v_pk_mul_f32 v[100:101], v[18:19], v[98:99]
	v_pk_mul_f32 v[102:103], v[16:17], v[96:97]
	v_pk_mul_f32 v[98:99], v[50:51], v[98:99]
	v_pk_mul_f32 v[96:97], v[78:79], v[96:97]
	v_pk_fma_f32 v[102:103], v[78:79], v[56:57], v[102:103] neg_lo:[0,0,1] neg_hi:[0,0,1]
	v_pk_fma_f32 v[100:101], v[50:51], v[74:75], v[100:101] neg_lo:[0,0,1] neg_hi:[0,0,1]
	v_pk_fma_f32 v[56:57], v[16:17], v[56:57], v[96:97]
	v_pk_fma_f32 v[74:75], v[18:19], v[74:75], v[98:99]
	v_pk_add_f32 v[6:7], v[40:41], v[6:7]
	v_pk_mul_f32 v[40:41], v[50:51], v[50:51]
	v_pk_mul_f32 v[70:71], v[78:79], v[78:79]
	v_pk_add_f32 v[30:31], v[30:31], v[74:75]
	v_pk_add_f32 v[28:29], v[28:29], v[56:57]
	v_pk_add_f32 v[50:51], v[50:51], v[50:51]
	v_pk_add_f32 v[56:57], v[78:79], v[78:79]
	v_mov_b32_dpp v74, v20 row_shr:2 row_mask:0xf bank_mask:0xf bound_ctrl:1
	v_mov_b32_dpp v75, v21 row_shr:2 row_mask:0xf bank_mask:0xf bound_ctrl:1
	v_mov_b32_dpp v78, v22 row_shr:2 row_mask:0xf bank_mask:0xf bound_ctrl:1
	v_mov_b32_dpp v79, v23 row_shr:2 row_mask:0xf bank_mask:0xf bound_ctrl:1
	v_pk_fma_f32 v[40:41], v[18:19], v[18:19], v[40:41] neg_lo:[1,0,0] neg_hi:[1,0,0]
	v_pk_fma_f32 v[70:71], v[16:17], v[16:17], v[70:71] neg_lo:[1,0,0] neg_hi:[1,0,0]
	v_pk_mul_f32 v[18:19], v[18:19], v[50:51]
	v_pk_mul_f32 v[16:17], v[16:17], v[56:57]
	v_mov_b32_dpp v50, v52 row_shr:2 row_mask:0xf bank_mask:0xf bound_ctrl:1
	v_mov_b32_dpp v51, v53 row_shr:2 row_mask:0xf bank_mask:0xf bound_ctrl:1
	v_mov_b32_dpp v56, v54 row_shr:2 row_mask:0xf bank_mask:0xf bound_ctrl:1
	v_mov_b32_dpp v57, v55 row_shr:2 row_mask:0xf bank_mask:0xf bound_ctrl:1
	v_pk_mul_f32 v[96:97], v[10:11], v[78:79]
	v_pk_mul_f32 v[98:99], v[8:9], v[74:75]
	v_pk_fma_f32 v[96:97], v[48:49], v[56:57], v[96:97] neg_lo:[0,0,1] neg_hi:[0,0,1]
	v_pk_fma_f32 v[98:99], v[76:77], v[50:51], v[98:99] neg_lo:[0,0,1] neg_hi:[0,0,1]
	v_pk_add_f32 v[96:97], v[54:55], v[96:97]
	v_pk_add_f32 v[98:99], v[52:53], v[98:99]
	v_pk_mul_f32 v[52:53], v[48:49], v[78:79]
	v_pk_mul_f32 v[54:55], v[76:77], v[74:75]
	v_pk_fma_f32 v[52:53], v[10:11], v[56:57], v[52:53]
	v_pk_fma_f32 v[50:51], v[8:9], v[50:51], v[54:55]
	v_pk_add_f32 v[46:47], v[46:47], v[60:61]
	v_pk_mul_f32 v[38:39], v[48:49], v[48:49]
	v_pk_mul_f32 v[60:61], v[76:77], v[76:77]
	v_pk_add_f32 v[22:23], v[22:23], v[52:53]
	v_pk_add_f32 v[20:21], v[20:21], v[50:51]
	v_pk_add_f32 v[48:49], v[48:49], v[48:49]
	v_pk_add_f32 v[50:51], v[76:77], v[76:77]
	v_mov_b32_dpp v52, v12 row_shr:2 row_mask:0xf bank_mask:0xf bound_ctrl:1
	v_mov_b32_dpp v53, v13 row_shr:2 row_mask:0xf bank_mask:0xf bound_ctrl:1
	v_mov_b32_dpp v54, v14 row_shr:2 row_mask:0xf bank_mask:0xf bound_ctrl:1
; template <int CTRL> DI f32x4 dpp4(const f32x4 v) { const float a0 = v[0], a1 = v[1], a2 = v[2], a3 = v[3]; const float b0 = DPPF(a0, CTRL), b1 = DPPF(a1, CTRL), b2 = DPPF(a2, CTRL), b3 = DPPF(a3, CTRL); return (f32x4){b0, b1, b2, b3}; }
; template <int D>
; DI void s5_scan_step(f32x4 (&Yr)[4], f32x4 (&Yi)[4], f32x4 (&Ar)[4], f32x4 (&Ai)[4]) {
; #pragma unroll
;     for (int m = 0; m < 4; ++m) {
;         const f32x4 sr = dpp4<0x110 + D>(Yr[m]), si = dpp4<0x110 + D>(Yi[m]);
;         Yr[m] += Ar[m] * sr - Ai[m] * si; Yi[m] += Ar[m] * si + Ai[m] * sr;
;         const f32x4 a2r = Ar[m] * Ar[m] - Ai[m] * Ai[m], a2i = 2.f * Ar[m] * Ai[m]; Ar[m] = a2r; Ai[m] = a2i; }
; }
	v_mov_b32_dpp v55, v15 row_shr:2 row_mask:0xf bank_mask:0xf bound_ctrl:1
	v_pk_fma_f32 v[38:39], v[10:11], v[10:11], v[38:39] neg_lo:[1,0,0] neg_hi:[1,0,0]
	v_pk_fma_f32 v[60:61], v[8:9], v[8:9], v[60:61] neg_lo:[1,0,0] neg_hi:[1,0,0]
	v_pk_mul_f32 v[10:11], v[10:11], v[48:49]
	v_pk_mul_f32 v[8:9], v[8:9], v[50:51]
	v_mov_b32_dpp v48, v68 row_shr:2 row_mask:0xf bank_mask:0xf bound_ctrl:1
	v_mov_b32_dpp v49, v69 row_shr:2 row_mask:0xf bank_mask:0xf bound_ctrl:1
	v_mov_b32_dpp v50, v62 row_shr:2 row_mask:0xf bank_mask:0xf bound_ctrl:1
	v_mov_b32_dpp v51, v63 row_shr:2 row_mask:0xf bank_mask:0xf bound_ctrl:1
	v_pk_mul_f32 v[56:57], v[2:3], v[54:55]
	v_pk_mul_f32 v[74:75], v[0:1], v[52:53]
	v_pk_mul_f32 v[54:55], v[32:33], v[54:55]
	v_pk_mul_f32 v[52:53], v[34:35], v[52:53]
	v_pk_add_f32 v[44:45], v[44:45], v[58:59]
	v_pk_mul_f32 v[36:37], v[32:33], v[32:33]
	v_pk_mul_f32 v[58:59], v[34:35], v[34:35]
	v_pk_fma_f32 v[74:75], v[34:35], v[48:49], v[74:75] neg_lo:[0,0,1] neg_hi:[0,0,1]
	v_pk_fma_f32 v[56:57], v[32:33], v[50:51], v[56:57] neg_lo:[0,0,1] neg_hi:[0,0,1]
	v_pk_fma_f32 v[48:49], v[0:1], v[48:49], v[52:53]
	v_pk_fma_f32 v[50:51], v[2:3], v[50:51], v[54:55]
	v_pk_add_f32 v[32:33], v[32:33], v[32:33]
	v_pk_add_f32 v[34:35], v[34:35], v[34:35]
	v_pk_add_f32 v[66:67], v[66:67], v[100:101]
	v_pk_add_f32 v[64:65], v[64:65], v[102:103]
	v_pk_add_f32 v[68:69], v[68:69], v[74:75]
	v_pk_add_f32 v[14:15], v[14:15], v[50:51]
	v_pk_add_f32 v[12:13], v[12:13], v[48:49]
	v_pk_fma_f32 v[36:37], v[2:3], v[2:3], v[36:37] neg_lo:[1,0,0] neg_hi:[1,0,0]
	v_pk_fma_f32 v[74:75], v[0:1], v[0:1], v[58:59] neg_lo:[1,0,0] neg_hi:[1,0,0]
	v_pk_mul_f32 v[2:3], v[2:3], v[32:33]
	v_pk_mul_f32 v[0:1], v[0:1], v[34:35]
	v_pk_add_f32 v[62:63], v[62:63], v[56:57]
	v_mov_b32_dpp v48, v4 row_shr:4 row_mask:0xf bank_mask:0xf bound_ctrl:1
	v_mov_b32_dpp v49, v5 row_shr:4 row_mask:0xf bank_mask:0xf bound_ctrl:1
	v_mov_b32_dpp v50, v6 row_shr:4 row_mask:0xf bank_mask:0xf bound_ctrl:1
	v_mov_b32_dpp v51, v7 row_shr:4 row_mask:0xf bank_mask:0xf bound_ctrl:1
	v_mov_b32_dpp v32, v46 row_shr:4 row_mask:0xf bank_mask:0xf bound_ctrl:1
	v_mov_b32_dpp v33, v47 row_shr:4 row_mask:0xf bank_mask:0xf bound_ctrl:1
	v_mov_b32_dpp v34, v44 row_shr:4 row_mask:0xf bank_mask:0xf bound_ctrl:1
	v_mov_b32_dpp v35, v45 row_shr:4 row_mask:0xf bank_mask:0xf bound_ctrl:1
	v_pk_mul_f32 v[52:53], v[26:27], v[50:51]
	v_pk_mul_f32 v[54:55], v[24:25], v[48:49]
	v_pk_mul_f32 v[50:51], v[42:43], v[50:51]
	v_pk_mul_f32 v[48:49], v[72:73], v[48:49]
	v_pk_fma_f32 v[54:55], v[72:73], v[32:33], v[54:55] neg_lo:[0,0,1] neg_hi:[0,0,1]
	v_pk_fma_f32 v[52:53], v[42:43], v[34:35], v[52:53] neg_lo:[0,0,1] neg_hi:[0,0,1]
	v_pk_fma_f32 v[32:33], v[24:25], v[32:33], v[48:49]
	v_pk_fma_f32 v[34:35], v[26:27], v[34:35], v[50:51]
	v_pk_add_f32 v[4:5], v[4:5], v[32:33]
	v_pk_add_f32 v[6:7], v[6:7], v[34:35]
	v_pk_mul_f32 v[32:33], v[26:27], v[26:27]
	v_pk_mul_f32 v[34:35], v[24:25], v[24:25]
	v_pk_fma_f32 v[48:49], v[42:43], v[42:43], v[32:33] neg_lo:[0,0,1] neg_hi:[0,0,1]
	v_pk_fma_f32 v[50:51], v[72:73], v[72:73], v[34:35] neg_lo:[0,0,1] neg_hi:[0,0,1]
	v_pk_add_f32 v[32:33], v[42:43], v[42:43]
	v_pk_add_f32 v[34:35], v[72:73], v[72:73]
	v_pk_add_f32 v[44:45], v[44:45], v[52:53]
	v_pk_add_f32 v[46:47], v[46:47], v[54:55]
	v_pk_mul_f32 v[52:53], v[26:27], v[32:33]
	v_pk_mul_f32 v[54:55], v[24:25], v[34:35]
	v_mov_b32_dpp v32, v28 row_shr:4 row_mask:0xf bank_mask:0xf bound_ctrl:1
	v_mov_b32_dpp v33, v29 row_shr:4 row_mask:0xf bank_mask:0xf bound_ctrl:1
	v_mov_b32_dpp v34, v30 row_shr:4 row_mask:0xf bank_mask:0xf bound_ctrl:1
	v_mov_b32_dpp v35, v31 row_shr:4 row_mask:0xf bank_mask:0xf bound_ctrl:1
	v_mov_b32_dpp v24, v64 row_shr:4 row_mask:0xf bank_mask:0xf bound_ctrl:1
	v_mov_b32_dpp v25, v65 row_shr:4 row_mask:0xf bank_mask:0xf bound_ctrl:1
	v_mov_b32_dpp v26, v66 row_shr:4 row_mask:0xf bank_mask:0xf bound_ctrl:1
	v_mov_b32_dpp v27, v67 row_shr:4 row_mask:0xf bank_mask:0xf bound_ctrl:1
	v_pk_mul_f32 v[42:43], v[18:19], v[34:35]
	v_pk_mul_f32 v[56:57], v[16:17], v[32:33]
	v_pk_mul_f32 v[34:35], v[40:41], v[34:35]
	v_pk_mul_f32 v[32:33], v[70:71], v[32:33]
	v_pk_fma_f32 v[56:57], v[70:71], v[24:25], v[56:57] neg_lo:[0,0,1] neg_hi:[0,0,1]
	v_pk_fma_f32 v[42:43], v[40:41], v[26:27], v[42:43] neg_lo:[0,0,1] neg_hi:[0,0,1]
	v_pk_fma_f32 v[24:25], v[16:17], v[24:25], v[32:33]
	v_pk_fma_f32 v[26:27], v[18:19], v[26:27], v[34:35]
	v_pk_add_f32 v[24:25], v[28:29], v[24:25]
	v_pk_add_f32 v[26:27], v[30:31], v[26:27]
	v_pk_mul_f32 v[28:29], v[18:19], v[18:19]
	v_pk_mul_f32 v[30:31], v[16:17], v[16:17]
	v_pk_add_f32 v[72:73], v[64:65], v[56:57]
	v_pk_fma_f32 v[56:57], v[40:41], v[40:41], v[28:29] neg_lo:[0,0,1] neg_hi:[0,0,1]
	v_pk_fma_f32 v[58:59], v[70:71], v[70:71], v[30:31] neg_lo:[0,0,1] neg_hi:[0,0,1]
	v_pk_add_f32 v[28:29], v[40:41], v[40:41]
	v_pk_add_f32 v[30:31], v[70:71], v[70:71]
	v_pk_add_f32 v[42:43], v[66:67], v[42:43]
	v_pk_mul_f32 v[64:65], v[18:19], v[28:29]
	v_pk_mul_f32 v[66:67], v[16:17], v[30:31]
	v_mov_b32_dpp v28, v20 row_shr:4 row_mask:0xf bank_mask:0xf bound_ctrl:1
	v_mov_b32_dpp v29, v21 row_shr:4 row_mask:0xf bank_mask:0xf bound_ctrl:1
	v_mov_b32_dpp v30, v22 row_shr:4 row_mask:0xf bank_mask:0xf bound_ctrl:1
	v_mov_b32_dpp v31, v23 row_shr:4 row_mask:0xf bank_mask:0xf bound_ctrl:1
	v_mov_b32_dpp v16, v98 row_shr:4 row_mask:0xf bank_mask:0xf bound_ctrl:1
	v_mov_b32_dpp v17, v99 row_shr:4 row_mask:0xf bank_mask:0xf bound_ctrl:1
	v_mov_b32_dpp v18, v96 row_shr:4 row_mask:0xf bank_mask:0xf bound_ctrl:1
	v_mov_b32_dpp v19, v97 row_shr:4 row_mask:0xf bank_mask:0xf bound_ctrl:1
	v_pk_mul_f32 v[32:33], v[10:11], v[30:31]
; template <int CTRL> DI f32x4 dpp4(const f32x4 v) { const float a0 = v[0], a1 = v[1], a2 = v[2], a3 = v[3]; const float b0 = DPPF(a0, CTRL), b1 = DPPF(a1, CTRL), b2 = DPPF(a2, CTRL), b3 = DPPF(a3, CTRL); return (f32x4){b0, b1, b2, b3}; }
; template <int D>
; DI void s5_scan_step(f32x4 (&Yr)[4], f32x4 (&Yi)[4], f32x4 (&Ar)[4], f32x4 (&Ai)[4]) {
; #pragma unroll
;     for (int m = 0; m < 4; ++m) {
;         const f32x4 sr = dpp4<0x110 + D>(Yr[m]), si = dpp4<0x110 + D>(Yi[m]);
;         Yr[m] += Ar[m] * sr - Ai[m] * si; Yi[m] += Ar[m] * si + Ai[m] * sr;
;         const f32x4 a2r = Ar[m] * Ar[m] - Ai[m] * Ai[m], a2i = 2.f * Ar[m] * Ai[m]; Ar[m] = a2r; Ai[m] = a2i; }
; }
	v_pk_mul_f32 v[34:35], v[8:9], v[28:29]
	v_pk_mul_f32 v[30:31], v[38:39], v[30:31]
	v_pk_mul_f32 v[28:29], v[60:61], v[28:29]
	v_pk_fma_f32 v[34:35], v[60:61], v[16:17], v[34:35] neg_lo:[0,0,1] neg_hi:[0,0,1]
	v_pk_fma_f32 v[32:33], v[38:39], v[18:19], v[32:33] neg_lo:[0,0,1] neg_hi:[0,0,1]
	v_pk_fma_f32 v[16:17], v[8:9], v[16:17], v[28:29]
	v_pk_fma_f32 v[18:19], v[10:11], v[18:19], v[30:31]
	v_pk_add_f32 v[16:17], v[20:21], v[16:17]
	v_pk_add_f32 v[18:19], v[22:23], v[18:19]
	v_pk_mul_f32 v[20:21], v[10:11], v[10:11]
	v_pk_mul_f32 v[22:23], v[8:9], v[8:9]
	v_pk_fma_f32 v[116:117], v[38:39], v[38:39], v[20:21] neg_lo:[0,0,1] neg_hi:[0,0,1]
	v_pk_fma_f32 v[118:119], v[60:61], v[60:61], v[22:23] neg_lo:[0,0,1] neg_hi:[0,0,1]
	v_pk_add_f32 v[20:21], v[38:39], v[38:39]
	v_pk_add_f32 v[22:23], v[60:61], v[60:61]
	v_pk_mul_f32 v[120:121], v[10:11], v[20:21]
	v_pk_mul_f32 v[122:123], v[8:9], v[22:23]
	v_mov_b32_dpp v20, v12 row_shr:4 row_mask:0xf bank_mask:0xf bound_ctrl:1
	v_mov_b32_dpp v21, v13 row_shr:4 row_mask:0xf bank_mask:0xf bound_ctrl:1
	v_mov_b32_dpp v22, v14 row_shr:4 row_mask:0xf bank_mask:0xf bound_ctrl:1
	v_mov_b32_dpp v23, v15 row_shr:4 row_mask:0xf bank_mask:0xf bound_ctrl:1
	v_mov_b32_dpp v8, v68 row_shr:4 row_mask:0xf bank_mask:0xf bound_ctrl:1
	v_mov_b32_dpp v9, v69 row_shr:4 row_mask:0xf bank_mask:0xf bound_ctrl:1
	v_mov_b32_dpp v10, v62 row_shr:4 row_mask:0xf bank_mask:0xf bound_ctrl:1
	v_mov_b32_dpp v11, v63 row_shr:4 row_mask:0xf bank_mask:0xf bound_ctrl:1
	v_pk_mul_f32 v[28:29], v[2:3], v[22:23]
	v_pk_mul_f32 v[30:31], v[0:1], v[20:21]
	v_pk_mul_f32 v[22:23], v[36:37], v[22:23]
	v_pk_mul_f32 v[20:21], v[74:75], v[20:21]
	v_pk_fma_f32 v[30:31], v[74:75], v[8:9], v[30:31] neg_lo:[0,0,1] neg_hi:[0,0,1]
	v_pk_fma_f32 v[28:29], v[36:37], v[10:11], v[28:29] neg_lo:[0,0,1] neg_hi:[0,0,1]
	v_pk_fma_f32 v[8:9], v[0:1], v[8:9], v[20:21]
	v_pk_fma_f32 v[10:11], v[2:3], v[10:11], v[22:23]
	v_pk_add_f32 v[38:39], v[62:63], v[28:29]
	v_pk_add_f32 v[60:61], v[14:15], v[10:11]
	v_pk_add_f32 v[62:63], v[12:13], v[8:9]
	v_pk_mul_f32 v[8:9], v[2:3], v[2:3]
	v_pk_mul_f32 v[10:11], v[0:1], v[0:1]
	v_pk_fma_f32 v[124:125], v[36:37], v[36:37], v[8:9] neg_lo:[0,0,1] neg_hi:[0,0,1]
	v_pk_fma_f32 v[126:127], v[74:75], v[74:75], v[10:11] neg_lo:[0,0,1] neg_hi:[0,0,1]
	v_pk_add_f32 v[8:9], v[36:37], v[36:37]
	v_pk_add_f32 v[10:11], v[74:75], v[74:75]
	v_pk_mul_f32 v[130:131], v[2:3], v[8:9]
	v_pk_mul_f32 v[132:133], v[0:1], v[10:11]
	v_pk_add_f32 v[32:33], v[96:97], v[32:33]
	v_pk_add_f32 v[34:35], v[98:99], v[34:35]
	v_pk_add_f32 v[40:41], v[68:69], v[30:31]
	v_mov_b32_dpp v8, v4 row_shr:8 row_mask:0xf bank_mask:0xf bound_ctrl:1
	v_mov_b32_dpp v9, v5 row_shr:8 row_mask:0xf bank_mask:0xf bound_ctrl:1
	v_mov_b32_dpp v10, v6 row_shr:8 row_mask:0xf bank_mask:0xf bound_ctrl:1
	v_mov_b32_dpp v11, v7 row_shr:8 row_mask:0xf bank_mask:0xf bound_ctrl:1
	v_mov_b32_dpp v0, v46 row_shr:8 row_mask:0xf bank_mask:0xf bound_ctrl:1
	v_mov_b32_dpp v1, v47 row_shr:8 row_mask:0xf bank_mask:0xf bound_ctrl:1
	v_mov_b32_dpp v2, v44 row_shr:8 row_mask:0xf bank_mask:0xf bound_ctrl:1
	v_mov_b32_dpp v3, v45 row_shr:8 row_mask:0xf bank_mask:0xf bound_ctrl:1
	v_pk_mul_f32 v[12:13], v[52:53], v[10:11]
	v_pk_mul_f32 v[14:15], v[54:55], v[8:9]
	v_pk_mul_f32 v[10:11], v[48:49], v[10:11]
	v_pk_mul_f32 v[8:9], v[50:51], v[8:9]
	v_pk_fma_f32 v[20:21], v[50:51], v[0:1], v[14:15] neg_lo:[0,0,1] neg_hi:[0,0,1]
	v_pk_fma_f32 v[12:13], v[48:49], v[2:3], v[12:13] neg_lo:[0,0,1] neg_hi:[0,0,1]
	v_pk_fma_f32 v[0:1], v[54:55], v[0:1], v[8:9]
	v_pk_fma_f32 v[2:3], v[52:53], v[2:3], v[10:11]
	v_pk_add_f32 v[28:29], v[4:5], v[0:1]
	v_pk_add_f32 v[30:31], v[6:7], v[2:3]
	v_mov_b32_dpp v4, v24 row_shr:8 row_mask:0xf bank_mask:0xf bound_ctrl:1
	v_mov_b32_dpp v5, v25 row_shr:8 row_mask:0xf bank_mask:0xf bound_ctrl:1
	v_mov_b32_dpp v6, v26 row_shr:8 row_mask:0xf bank_mask:0xf bound_ctrl:1
; #define LAS __attribute__((address_space(3)))
; #define SB() __builtin_amdgcn_sched_barrier(0)
; template <bool POST>
; DI void s5_phase(const Frame& F, const CAS Args& a, int l, int first, int stride) {
;     ...
;         s5_scan_step<1>(Yr, Yi, Ar, Ai); SB(); s5_scan_step<2>(Yr, Yi, Ar, Ai); SB(); s5_scan_step<4>(Yr, Yi, Ar, Ai); SB(); s5_scan_step<8>(Yr, Yi, Ar, Ai); SB();
;         if (n == 15) {
; #pragma unroll
;             for (int m = 0; m < 4; ++m) { *(LAS f32x4*)(TW + w * 128 + 16 * m + 4 * kg) = Yr[m]; *(LAS f32x4*)(TW + w * 128 + 64 + 16 * m + 4 * kg) = Yi[m]; } }
	v_mov_b32_dpp v7, v27 row_shr:8 row_mask:0xf bank_mask:0xf bound_ctrl:1
	v_mov_b32_dpp v0, v72 row_shr:8 row_mask:0xf bank_mask:0xf bound_ctrl:1
	v_mov_b32_dpp v1, v73 row_shr:8 row_mask:0xf bank_mask:0xf bound_ctrl:1
	v_mov_b32_dpp v2, v42 row_shr:8 row_mask:0xf bank_mask:0xf bound_ctrl:1
	v_mov_b32_dpp v3, v43 row_shr:8 row_mask:0xf bank_mask:0xf bound_ctrl:1
	v_pk_mul_f32 v[8:9], v[64:65], v[6:7]
	v_pk_mul_f32 v[10:11], v[66:67], v[4:5]
	v_pk_add_f32 v[14:15], v[44:45], v[12:13]
	v_pk_add_f32 v[12:13], v[46:47], v[20:21]
	v_pk_fma_f32 v[20:21], v[58:59], v[0:1], v[10:11] neg_lo:[0,0,1] neg_hi:[0,0,1]
	v_pk_fma_f32 v[8:9], v[56:57], v[2:3], v[8:9] neg_lo:[0,0,1] neg_hi:[0,0,1]
	v_pk_mul_f32 v[6:7], v[56:57], v[6:7]
	v_pk_mul_f32 v[4:5], v[58:59], v[4:5]
	v_pk_add_f32 v[10:11], v[42:43], v[8:9]
	v_pk_add_f32 v[8:9], v[72:73], v[20:21]
	v_pk_fma_f32 v[0:1], v[66:67], v[0:1], v[4:5]
	v_pk_fma_f32 v[2:3], v[64:65], v[2:3], v[6:7]
	v_mov_b32_dpp v20, v16 row_shr:8 row_mask:0xf bank_mask:0xf bound_ctrl:1
	v_mov_b32_dpp v21, v17 row_shr:8 row_mask:0xf bank_mask:0xf bound_ctrl:1
	v_mov_b32_dpp v22, v18 row_shr:8 row_mask:0xf bank_mask:0xf bound_ctrl:1
	v_mov_b32_dpp v23, v19 row_shr:8 row_mask:0xf bank_mask:0xf bound_ctrl:1
	v_pk_add_f32 v[26:27], v[26:27], v[2:3]
	v_pk_add_f32 v[24:25], v[24:25], v[0:1]
	v_mov_b32_dpp v0, v34 row_shr:8 row_mask:0xf bank_mask:0xf bound_ctrl:1
	v_mov_b32_dpp v1, v35 row_shr:8 row_mask:0xf bank_mask:0xf bound_ctrl:1
	v_mov_b32_dpp v2, v32 row_shr:8 row_mask:0xf bank_mask:0xf bound_ctrl:1
	v_mov_b32_dpp v3, v33 row_shr:8 row_mask:0xf bank_mask:0xf bound_ctrl:1
	v_pk_mul_f32 v[4:5], v[120:121], v[22:23]
	v_pk_mul_f32 v[6:7], v[122:123], v[20:21]
	v_pk_fma_f32 v[4:5], v[116:117], v[2:3], v[4:5] neg_lo:[0,0,1] neg_hi:[0,0,1]
	v_pk_fma_f32 v[36:37], v[118:119], v[0:1], v[6:7] neg_lo:[0,0,1] neg_hi:[0,0,1]
	v_pk_mul_f32 v[22:23], v[116:117], v[22:23]
	v_pk_mul_f32 v[20:21], v[118:119], v[20:21]
	v_pk_add_f32 v[6:7], v[32:33], v[4:5]
	v_pk_add_f32 v[4:5], v[34:35], v[36:37]
	v_pk_fma_f32 v[0:1], v[122:123], v[0:1], v[20:21]
	v_pk_fma_f32 v[2:3], v[120:121], v[2:3], v[22:23]
	v_mov_b32_dpp v32, v62 row_shr:8 row_mask:0xf bank_mask:0xf bound_ctrl:1
	v_mov_b32_dpp v33, v63 row_shr:8 row_mask:0xf bank_mask:0xf bound_ctrl:1
	v_mov_b32_dpp v34, v60 row_shr:8 row_mask:0xf bank_mask:0xf bound_ctrl:1
	v_mov_b32_dpp v35, v61 row_shr:8 row_mask:0xf bank_mask:0xf bound_ctrl:1
	v_pk_add_f32 v[22:23], v[18:19], v[2:3]
	v_pk_add_f32 v[20:21], v[16:17], v[0:1]
	v_mov_b32_dpp v16, v40 row_shr:8 row_mask:0xf bank_mask:0xf bound_ctrl:1
	v_mov_b32_dpp v17, v41 row_shr:8 row_mask:0xf bank_mask:0xf bound_ctrl:1
	v_mov_b32_dpp v18, v38 row_shr:8 row_mask:0xf bank_mask:0xf bound_ctrl:1
	v_mov_b32_dpp v19, v39 row_shr:8 row_mask:0xf bank_mask:0xf bound_ctrl:1
	v_pk_mul_f32 v[0:1], v[130:131], v[34:35]
	v_pk_mul_f32 v[2:3], v[132:133], v[32:33]
	v_pk_mul_f32 v[34:35], v[124:125], v[34:35]
	v_pk_mul_f32 v[32:33], v[126:127], v[32:33]
	v_pk_fma_f32 v[36:37], v[126:127], v[16:17], v[2:3] neg_lo:[0,0,1] neg_hi:[0,0,1]
	v_pk_fma_f32 v[0:1], v[124:125], v[18:19], v[0:1] neg_lo:[0,0,1] neg_hi:[0,0,1]
	v_pk_fma_f32 v[16:17], v[132:133], v[16:17], v[32:33]
	v_pk_fma_f32 v[18:19], v[130:131], v[18:19], v[34:35]
	v_pk_add_f32 v[2:3], v[38:39], v[0:1]
	v_pk_add_f32 v[0:1], v[40:41], v[36:37]
	v_pk_add_f32 v[18:19], v[60:61], v[18:19]
	v_pk_add_f32 v[16:17], v[62:63], v[16:17]
	s_and_saveexec_b64 s[0:1], s[4:5]
	s_cbranch_execz .LBB0_798
	v_readlane_b32 s6, v253, 53
	s_add_i32 s6, s37, s6
	s_nop 0
	v_lshl_add_u32 v32, v80, 2, s6
	ds_write_b128 v32, v[12:15]
	ds_write_b128 v32, v[28:31] offset:256
	ds_write_b128 v32, v[8:11] offset:64
	ds_write_b128 v32, v[24:27] offset:320
	ds_write_b128 v32, v[4:7] offset:128
	ds_write_b128 v32, v[20:23] offset:384
	ds_write_b128 v32, v[0:3] offset:192
	ds_write_b128 v32, v[16:19] offset:448
